# stack: xattn (staging coalesced, QK/PV pipelined, dwordx4 stores, V hoist, async L1 invalidate) + FoX row-max via v_max3 chains + P0 wave sums via DPP + P4/FoX wait fixes
# speedup vs baseline: 1.0088x; 1.0069x over previous
.LBB0_748:
	s_waitcnt vmcnt(0)
	s_waitcnt vmcnt(0) lgkmcnt(0)
	s_barrier
	s_and_saveexec_b64 s[4:5], s[90:91]
	s_cbranch_execz .LBB0_750
	buffer_inv sc1
.LBB0_750:
	s_or_b64 exec, exec, s[4:5]
	v_lshlrev_b32_e32 v148, 12, v154
	v_mov_b32_e32 v149, 0
	v_and_b32_e32 v2, 7, v223
	v_lshl_add_u64 v[0:1], s[30:31], 0, v[148:149]
	s_mov_b64 s[4:5], 0x2a00000
	s_ashr_i32 s3, s26, 31
	s_ashr_i32 s27, s2, 31
	v_lshl_add_u64 v[150:151], v[0:1], 0, s[4:5]
	v_lshlrev_b32_e32 v0, 3, v2
	v_lshlrev_b32_e32 v1, 4, v2
	v_mul_u32_u24_e32 v2, 0x230, v154
	s_add_u32 s6, s30, 0x2f00000
	s_movk_i32 s4, 0x230
	v_add3_u32 v172, 0, v1, v2
	v_or_b32_e32 v2, v178, v152
	v_and_or_b32 v3, v153, 12, v177
	s_addc_u32 s7, s31, 0
	v_lshlrev_b32_e32 v177, 1, v3
	v_mad_u32_u24 v2, v2, s4, 0
	v_mov_b32_e32 v181, v149
	v_mul_u32_u24_e32 v1, 0x230, v176
	s_add_u32 s12, s30, 0xa000000
	v_add_u32_e32 v186, v2, v177
	v_add_u32_e32 v187, 0x10680, v2
	v_add_u32_e32 v188, 0x11800, v2
	v_add_u32_e32 v189, 0x12980, v2
	v_add_u32_e32 v190, 0x13b00, v2
	v_add_u32_e32 v191, 0x14c80, v2
	v_add_u32_e32 v192, 0x15e00, v2
	v_add_u32_e32 v193, 0x16f80, v2
	v_add_u32_e32 v194, 0x18100, v2
	v_add_u32_e32 v195, 0x19280, v2
	v_add_u32_e32 v196, 0x1a400, v2
	v_add_u32_e32 v197, 0x1b580, v2
	v_add_u32_e32 v198, 0x1c700, v2
	v_add_u32_e32 v199, 0x1d880, v2
	v_add_u32_e32 v200, 0x1ea00, v2
	v_add_u32_e32 v201, 0x1fb80, v2
	v_add_u32_e32 v202, 0x20d00, v2
	v_add_u32_e32 v203, 0x21e80, v2
	v_lshl_add_u64 v[2:3], s[30:31], 0, v[180:181]
	s_mov_b64 s[4:5], 0x8000080
	v_lshlrev_b32_e32 v148, 1, v0
	v_mbcnt_lo_u32_b32 v0, -1, 0
	s_mov_b32 s11, 0
	v_add_u32_e32 v173, 0x11800, v172
	v_add_u32_e32 v174, 0x11880, v172
	v_add_u32_e32 v175, 0x11900, v172
	v_add_u32_e32 v179, 0x11980, v172
	v_add_u32_e32 v182, 0x1a400, v172
	v_add_u32_e32 v183, 0x1a480, v172
	v_add_u32_e32 v184, 0x1a500, v172
	v_add_u32_e32 v185, 0x1a580, v172
	s_addc_u32 s13, s31, 0
	v_or_b32_e32 v204, 64, v177
	v_or_b32_e32 v205, 0x80, v177
	v_or_b32_e32 v206, 0xc0, v177
	v_or_b32_e32 v207, 0x100, v177
	v_or_b32_e32 v208, 0x140, v177
	v_or_b32_e32 v209, 0x180, v177
	v_or_b32_e32 v210, 0x1c0, v177
	v_add3_u32 v211, v1, v180, 0
	v_lshl_add_u64 v[152:153], v[2:3], 0, s[4:5]
	s_mov_b64 s[14:15], 0x100
	v_mov_b64_e32 v[154:155], 0x100
	v_mov_b64_e32 v[156:157], 0xff
	s_mov_b64 s[16:17], 0x40000
	s_mov_b32 s34, 0x40000
	s_mov_b64 s[18:19], 0x80000
	s_mov_b32 s35, 0x80000
	s_mov_b64 s[36:37], 0xc0000
	s_mov_b32 s48, 0xc0000
	v_mov_b32_e32 v180, 0x358637bd
	s_mov_b32 s49, 0x800000
	s_mov_b32 s50, 0xff800000
	s_mov_b64 s[38:39], 0x40800
	s_mov_b64 s[40:41], 0x80800
	s_mov_b64 s[44:45], 0xc0800
	v_lshlrev_b32_e32 v158, 1, v178
	v_mbcnt_hi_u32_b32 v178, -1, v0
	s_mov_b32 s51, 0
	s_barrier
	s_branch .LBB0_752
